# conversion queue re-balanced inside top-k phases: fast/slow boundary moved in top-k 0 and 2, top-k 1 fast blocks take 4096 items back from the layer-2 in-projection tail
# baseline (speedup 1.0000x reference)
.LBB0_696:
	s_cmpk_lt_u32 s2, 0x80
	s_cselect_b64 s[4:5], -1, 0
	s_cmpk_gt_u32 s2, 0x7f
	s_cselect_b64 s[10:11], -1, 0
	s_movk_i32 s3, 0x4000
	s_and_b64 s[6:7], s[10:11], exec
	s_cselect_b32 s12, s3, 0x6800
	s_movk_i32 s3, 0x6c00
	s_cselect_b32 s3, 0x6800, s3
	s_cmpk_eq_i32 s56, 0x100
	s_cselect_b64 s[6:7], -1, 0
	s_and_b64 s[8:9], s[6:7], exec
	s_cselect_b32 s3, s3, 0x6000
	s_cselect_b32 s18, s12, s54
	s_cmp_ge_u32 s18, s3
	s_movk_i32 s19, 0x6000
	s_waitcnt vmcnt(0)
	s_barrier
	s_cbranch_scc1 .LBB0_711
	v_readlane_b32 s8, v255, 7
	s_and_b32 s8, s8, 0x3f8
	v_readlane_b32 s13, v255, 6
	s_add_i32 s20, s13, s8
	s_lshl_b32 s21, s20, 1
	s_movk_i32 s12, 0x800
	s_and_b64 s[8:9], s[10:11], exec
	s_cselect_b32 s12, s12, 0x400
	s_and_b64 s[8:9], s[6:7], exec
	s_mul_i32 s8, s13, 0x2200
	s_cselect_b32 s22, s12, s55
	s_add_i32 s24, s8, 0
	v_cndmask_b32_e64 v2, 0, 1, s[4:5]
	v_and_b32_e32 v1, 63, v0
	s_mov_b32 s9, 0
	s_mov_b32 s23, 0x10000
	s_add_i32 s24, s24, 0x10000
	s_and_b64 s[10:11], s[10:11], s[6:7]
	v_cmp_ne_u32_e64 s[4:5], 1, v2
	v_mov_b32_e32 v3, 0
	s_movk_i32 s25, 0x2000
	s_movk_i32 s26, 0x4000
	s_mov_b32 s27, 0x8000
	s_mov_b32 s28, 0xa000
	s_mov_b32 s29, 0xc000
	s_mov_b32 s30, 0xe000
	s_mov_b32 s31, 0x12000
	s_mov_b32 s34, 0x14000
	s_mov_b32 s35, 0x16000
	s_mov_b32 s36, 0x18000
	s_mov_b32 s37, 0x1a000
	s_mov_b32 s38, 0x1c000
	s_mov_b32 s39, 0x1e000
	s_mov_b32 s41, 0x20000
	s_mov_b32 s42, 0x22000
	s_mov_b32 s43, 0x24000
	s_mov_b32 s45, 0x26000
	s_mov_b32 s46, 0x28000
	s_mov_b32 s47, 0x2a000
	s_mov_b32 s49, 0x2c000
	s_mov_b32 s50, 0x2e000
	s_mov_b32 s51, 0x30000
	s_mov_b32 s57, 0x32000
	s_mov_b32 s58, 0x34000
	s_mov_b32 s59, 0x36000
	s_mov_b32 s72, 0x38000
	s_mov_b32 s73, 0x3a000
	s_mov_b32 s78, 0x3c000
	s_mov_b32 s79, 0x3e000
	s_movk_i32 s86, 0x84
	s_branch .LBB0_699

.LBB0_1580:
	s_cmpk_lt_u32 s2, 0x80
	s_cselect_b64 s[4:5], -1, 0
	s_cmpk_gt_u32 s2, 0x7f
	s_cselect_b64 s[10:11], -1, 0
	s_mov_b32 s3, 0xc000
	s_and_b64 s[6:7], s[10:11], exec
	s_cselect_b32 s12, s3, 0xdc00
	s_add_i32 s13, s54, 0x6000
	s_cmpk_eq_i32 s56, 0x100
	s_cselect_b64 s[6:7], -1, 0
	s_mov_b32 s18, 0xc000
	s_and_b64 s[8:9], s[6:7], exec
	s_cselect_b32 s19, 0xdc00, s18
	s_cselect_b32 s20, s12, s13
	s_movk_i32 s3, 0x6000
	s_cmp_ge_u32 s20, s19
	s_waitcnt vmcnt(0)
	s_barrier
	s_cbranch_scc1 .LBB0_1595
	v_readlane_b32 s8, v255, 7
	s_and_b32 s8, s8, 0x3f8
	v_readlane_b32 s13, v255, 6
	s_add_i32 s21, s13, s8
	s_lshl_b32 s22, s21, 1
	s_movk_i32 s12, 0x800
	s_and_b64 s[8:9], s[10:11], exec
	s_cselect_b32 s12, s12, 0x400
	s_and_b64 s[8:9], s[6:7], exec
	s_mul_i32 s8, s13, 0x2200
	s_cselect_b32 s23, s12, s55
	s_add_i32 s25, s8, 0
	v_cndmask_b32_e64 v2, 0, 1, s[4:5]
	v_and_b32_e32 v1, 63, v0
	s_mov_b32 s9, 0
	s_mov_b32 s24, 0x10000
	s_add_i32 s25, s25, 0x10000
	s_and_b64 s[10:11], s[10:11], s[6:7]
	v_cmp_ne_u32_e64 s[4:5], 1, v2
	v_mov_b32_e32 v3, 0
	s_movk_i32 s26, 0x2000
	s_movk_i32 s27, 0x4000
	s_mov_b32 s28, 0x8000
	s_mov_b32 s29, 0xa000
	s_mov_b32 s30, 0xe000
	s_mov_b32 s31, 0x12000
	s_mov_b32 s34, 0x14000
	s_mov_b32 s35, 0x16000
	s_mov_b32 s36, 0x18000
	s_mov_b32 s37, 0x1a000
	s_mov_b32 s38, 0x1c000
	s_mov_b32 s39, 0x1e000
	s_mov_b32 s41, 0x20000
	s_mov_b32 s42, 0x22000
	s_mov_b32 s43, 0x24000
	s_mov_b32 s45, 0x26000
	s_mov_b32 s46, 0x28000
	s_mov_b32 s47, 0x2a000
	s_mov_b32 s49, 0x2c000
	s_mov_b32 s57, 0x2e000
	s_mov_b32 s58, 0x30000
	s_mov_b32 s59, 0x32000
	s_mov_b32 s72, 0x34000
	s_mov_b32 s73, 0x36000
	s_mov_b32 s78, 0x38000
	s_mov_b32 s79, 0x3a000
	s_mov_b32 s84, 0x3c000
	s_mov_b32 s85, 0x3e000
	s_movk_i32 s86, 0x84
	s_branch .LBB0_1583

.LBB0_1885:
	s_cmp_lt_i32 s61, 27
	s_cbranch_scc1 .LBB0_2670
	s_cmp_gt_i32 s60, 26
	s_cbranch_scc1 .LBB0_1959
	s_cmpk_lg_i32 s56, 0x100
	s_cselect_b64 s[4:5], -1, 0
	s_cmp_lt_i32 s2, 48
	s_cselect_b64 s[6:7], -1, 0
	s_or_b64 s[4:5], s[6:7], s[4:5]
	s_and_b64 vcc, exec, s[4:5]
	s_cbranch_vccnz .LBB0_1895
	s_add_i32 s3, s54, 0xda80
	s_cmp_gt_i32 s3, 0x10cff
	s_cbranch_scc1 .LBB0_1895
	v_readlane_b32 s4, v255, 6
	s_mulk_i32 s4, 0x2200
	s_add_i32 s11, s4, 0
	v_and_b32_e32 v1, 63, v0
	s_mov_b32 s5, 0
	s_mov_b32 s10, 0x10000
	s_add_i32 s11, s11, 0x10000
	s_lshl_b32 s12, s3, 1
	s_lshl_b32 s13, s3, 5
	s_waitcnt vmcnt(0)
	v_mov_b32_e32 v3, 0
	s_movk_i32 s14, 0x2000
	s_movk_i32 s15, 0x4000
	s_movk_i32 s16, 0x6000
	s_mov_b32 s17, 0x8000
	s_mov_b32 s18, 0xa000
	s_mov_b32 s19, 0xc000
	s_mov_b32 s20, 0xe000
	s_mov_b32 s21, 0x12000
	s_mov_b32 s22, 0x14000
	s_mov_b32 s23, 0x16000
	s_mov_b32 s24, 0x18000
	s_mov_b32 s25, 0x1a000
	s_mov_b32 s26, 0x1c000
	s_mov_b32 s27, 0x1e000
	s_mov_b32 s28, 0x20000
	s_mov_b32 s29, 0x22000
	s_mov_b32 s30, 0x24000
	s_mov_b32 s31, 0x26000
	s_mov_b32 s34, 0x28000
	s_mov_b32 s35, 0x2a000
	s_mov_b32 s36, 0x2c000
	s_mov_b32 s37, 0x2e000
	s_mov_b32 s38, 0x30000
	s_mov_b32 s39, 0x32000
	s_mov_b32 s41, 0x34000
	s_mov_b32 s42, 0x36000
	s_mov_b32 s43, 0x38000
	s_mov_b32 s45, 0x3a000
	s_mov_b32 s46, 0x3c000
	s_mov_b32 s47, 0x3e000
	s_movk_i32 s49, 0x84
	s_movk_i32 s50, 0xc8
	s_branch .LBB0_1891

.LBB0_2349:
	s_cmpk_lt_u32 s2, 0x80
	s_cselect_b64 s[4:5], -1, 0
	s_cmpk_gt_u32 s2, 0x7f
	s_cselect_b64 s[10:11], -1, 0
	s_mov_b32 s3, 0x10d00
	s_and_b64 s[6:7], s[10:11], exec
	s_cselect_b32 s12, s3, 0x13500
	s_mov_b32 s3, 0x13900
	s_cselect_b32 s13, 0x13500, s3
	s_add_i32 s14, s54, 0xc000
	s_cmpk_eq_i32 s56, 0x100
	s_cselect_b64 s[6:7], -1, 0
	s_and_b64 s[8:9], s[6:7], exec
	s_cselect_b32 s18, s13, 0x12000
	s_cselect_b32 s19, s12, s14
	s_mov_b32 s3, 0xc000
	s_cmp_ge_u32 s19, s18
	s_mov_b32 s20, 0x12000
	s_waitcnt vmcnt(0)
	s_barrier
	s_cbranch_scc1 .LBB0_2364
	v_readlane_b32 s8, v255, 7
	s_and_b32 s8, s8, 0x3f8
	v_readlane_b32 s13, v255, 6
	s_add_i32 s21, s13, s8
	s_lshl_b32 s22, s21, 1
	s_movk_i32 s12, 0x800
	s_and_b64 s[8:9], s[10:11], exec
	s_cselect_b32 s12, s12, 0x400
	s_and_b64 s[8:9], s[6:7], exec
	s_mul_i32 s8, s13, 0x2200
	s_cselect_b32 s23, s12, s55
	s_add_i32 s25, s8, 0
	v_cndmask_b32_e64 v2, 0, 1, s[4:5]
	v_and_b32_e32 v1, 63, v0
	s_mov_b32 s9, 0
	s_mov_b32 s24, 0x10000
	s_add_i32 s25, s25, 0x10000
	s_and_b64 s[10:11], s[10:11], s[6:7]
	v_cmp_ne_u32_e64 s[4:5], 1, v2
	v_mov_b32_e32 v3, 0
	s_movk_i32 s26, 0x2000
	s_movk_i32 s27, 0x4000
	s_movk_i32 s28, 0x6000
	s_mov_b32 s29, 0x8000
	s_mov_b32 s30, 0xa000
	s_mov_b32 s31, 0xe000
	s_mov_b32 s34, 0x14000
	s_mov_b32 s35, 0x16000
	s_mov_b32 s36, 0x18000
	s_mov_b32 s37, 0x1a000
	s_mov_b32 s38, 0x1c000
	s_mov_b32 s39, 0x1e000
	s_mov_b32 s41, 0x20000
	s_mov_b32 s42, 0x22000
	s_mov_b32 s43, 0x24000
	s_mov_b32 s45, 0x26000
	s_mov_b32 s46, 0x28000
	s_mov_b32 s47, 0x2a000
	s_mov_b32 s49, 0x2c000
	s_mov_b32 s57, 0x2e000
	s_mov_b32 s58, 0x30000
	s_mov_b32 s59, 0x32000
	s_mov_b32 s72, 0x34000
	s_mov_b32 s73, 0x36000
	s_mov_b32 s78, 0x38000
	s_mov_b32 s79, 0x3a000
	s_mov_b32 s84, 0x3c000
	s_mov_b32 s85, 0x3e000
	s_movk_i32 s86, 0x84
	s_branch .LBB0_2352
